# in-proj SiLU gate epilogues: v*rcp(1+exp(-v)) with f32 v_rcp (1 ulp) instead of the 12-op IEEE division expansion; everything else as the pair-tile version
# speedup vs baseline: 1.3031x; 1.0062x over previous
.LBB0_216:
	s_andn2_b64 vcc, exec, s[84:85]
	s_cbranch_vccnz .LBB0_218
	v_mov_b32_e32 v0, v151
	s_mov_b32 s4, 0xfffffc0
	v_and_b32_e32 v66, 64, v0
	v_and_b32_e32 v67, 15, v0
	v_lshrrev_b32_e32 v0, 1, v0
	v_and_or_b32 v67, v0, s4, v67
	v_and_b32_e32 v0, 24, v0
	v_lshl_or_b32 v0, v66, 1, v0
	s_movk_i32 s4, 0x110
	v_mad_u64_u32 v[66:67], s[4:5], v67, s4, v[0:1]
	v_mul_f32_e32 v0, 0xbfb8aa3b, v62
	v_exp_f32_e32 v68, v0
	v_mul_f32_e32 v0, 0xbfb8aa3b, v63
	v_exp_f32_e32 v69, v0
	s_nop 0
	v_pk_add_f32 v[68:69], v[68:69], 1.0 op_sel_hi:[1,0]
	s_nop 0
	v_rcp_f32_e32 v0, v69
	s_nop 0
	v_mul_f32_e32 v0, v63, v0
	v_rcp_f32_e32 v63, v68
	s_nop 0
	v_mul_f32_e32 v62, v62, v63
	v_cvt_pk_bf16_f32 v62, v62, v0
	v_mul_f32_e32 v0, 0xbfb8aa3b, v64
	v_exp_f32_e32 v68, v0
	v_mul_f32_e32 v0, 0xbfb8aa3b, v65
	v_exp_f32_e32 v69, v0
	s_nop 0
	v_pk_add_f32 v[68:69], v[68:69], 1.0 op_sel_hi:[1,0]
	s_nop 0
	v_rcp_f32_e32 v0, v69
	s_nop 0
	v_mul_f32_e32 v0, v65, v0
	v_rcp_f32_e32 v63, v68
	s_nop 0
	v_mul_f32_e32 v63, v64, v63
	v_cvt_pk_bf16_f32 v63, v63, v0
	v_mul_f32_e32 v0, 0xbfb8aa3b, v58
	v_exp_f32_e32 v64, v0
	v_mul_f32_e32 v0, 0xbfb8aa3b, v59
	v_exp_f32_e32 v65, v0
	s_nop 0
	v_pk_add_f32 v[64:65], v[64:65], 1.0 op_sel_hi:[1,0]
	s_nop 0
	v_rcp_f32_e32 v0, v65
	s_nop 0
	v_mul_f32_e32 v0, v59, v0
	v_rcp_f32_e32 v59, v64
	s_nop 0
	v_mul_f32_e32 v58, v58, v59
	v_cvt_pk_bf16_f32 v58, v58, v0
	v_mul_f32_e32 v0, 0xbfb8aa3b, v60
	v_exp_f32_e32 v64, v0
	v_mul_f32_e32 v0, 0xbfb8aa3b, v61
	v_exp_f32_e32 v65, v0
	s_nop 0
	v_pk_add_f32 v[64:65], v[64:65], 1.0 op_sel_hi:[1,0]
	s_nop 0
	v_rcp_f32_e32 v0, v65
	s_nop 0
	v_mul_f32_e32 v0, v61, v0
	v_rcp_f32_e32 v59, v64
	s_nop 0
	v_mul_f32_e32 v59, v60, v59
	v_cvt_pk_bf16_f32 v59, v59, v0
	v_mul_f32_e32 v0, 0xbfb8aa3b, v54
	ds_write2_b64 v66, v[62:63], v[58:59] offset1:4
	v_exp_f32_e32 v58, v0
	v_mul_f32_e32 v0, 0xbfb8aa3b, v55
	v_exp_f32_e32 v59, v0
	s_nop 0
	v_pk_add_f32 v[58:59], v[58:59], 1.0 op_sel_hi:[1,0]
	s_nop 0
	v_rcp_f32_e32 v0, v59
	s_nop 0
	v_mul_f32_e32 v0, v55, v0
	v_rcp_f32_e32 v55, v58
	s_nop 0
	v_mul_f32_e32 v54, v54, v55
	v_cvt_pk_bf16_f32 v54, v54, v0
	v_mul_f32_e32 v0, 0xbfb8aa3b, v56
	v_exp_f32_e32 v58, v0
	v_mul_f32_e32 v0, 0xbfb8aa3b, v57
	v_exp_f32_e32 v59, v0
	s_nop 0
	v_pk_add_f32 v[58:59], v[58:59], 1.0 op_sel_hi:[1,0]
	s_nop 0
	v_rcp_f32_e32 v0, v59
	s_nop 0
	v_mul_f32_e32 v0, v57, v0
	v_rcp_f32_e32 v55, v58
	s_nop 0
	v_mul_f32_e32 v55, v56, v55
	v_cvt_pk_bf16_f32 v55, v55, v0
	v_mul_f32_e32 v0, 0xbfb8aa3b, v50
	v_exp_f32_e32 v56, v0
	v_mul_f32_e32 v0, 0xbfb8aa3b, v51
	v_exp_f32_e32 v57, v0
	s_nop 0
	v_pk_add_f32 v[56:57], v[56:57], 1.0 op_sel_hi:[1,0]
	s_nop 0
	v_rcp_f32_e32 v0, v57
	s_nop 0
	v_mul_f32_e32 v0, v51, v0
	v_rcp_f32_e32 v51, v56
	s_nop 0
	v_mul_f32_e32 v50, v50, v51
	v_cvt_pk_bf16_f32 v50, v50, v0
	v_mul_f32_e32 v0, 0xbfb8aa3b, v52
	v_exp_f32_e32 v56, v0
	v_mul_f32_e32 v0, 0xbfb8aa3b, v53
	v_exp_f32_e32 v57, v0
	s_nop 0
	v_pk_add_f32 v[56:57], v[56:57], 1.0 op_sel_hi:[1,0]
	s_nop 0
	v_rcp_f32_e32 v0, v57
	s_nop 0
	v_mul_f32_e32 v0, v53, v0
	v_rcp_f32_e32 v51, v56
	s_nop 0
	v_mul_f32_e32 v51, v52, v51
	v_cvt_pk_bf16_f32 v51, v51, v0
	v_mul_f32_e32 v0, 0xbfb8aa3b, v46
	ds_write2_b64 v66, v[54:55], v[50:51] offset0:8 offset1:12
	v_exp_f32_e32 v50, v0
	v_mul_f32_e32 v0, 0xbfb8aa3b, v47
	v_exp_f32_e32 v51, v0
	s_nop 0
	v_pk_add_f32 v[50:51], v[50:51], 1.0 op_sel_hi:[1,0]
	s_nop 0
	v_rcp_f32_e32 v0, v51
	s_nop 0
	v_mul_f32_e32 v0, v47, v0
	v_rcp_f32_e32 v47, v50
	s_nop 0
	v_mul_f32_e32 v46, v46, v47
	v_cvt_pk_bf16_f32 v46, v46, v0
	v_mul_f32_e32 v0, 0xbfb8aa3b, v48
	v_exp_f32_e32 v50, v0
	v_mul_f32_e32 v0, 0xbfb8aa3b, v49
	v_exp_f32_e32 v51, v0
	s_nop 0
	v_pk_add_f32 v[50:51], v[50:51], 1.0 op_sel_hi:[1,0]
	s_nop 0
	v_rcp_f32_e32 v0, v51
	s_nop 0
	v_mul_f32_e32 v0, v49, v0
	v_rcp_f32_e32 v47, v50
	s_nop 0
	v_mul_f32_e32 v47, v48, v47
	v_cvt_pk_bf16_f32 v47, v47, v0
	v_mul_f32_e32 v0, 0xbfb8aa3b, v42
	v_exp_f32_e32 v48, v0
	v_mul_f32_e32 v0, 0xbfb8aa3b, v43
	v_exp_f32_e32 v49, v0
	s_nop 0
	v_pk_add_f32 v[48:49], v[48:49], 1.0 op_sel_hi:[1,0]
	s_nop 0
	v_rcp_f32_e32 v0, v49
	s_nop 0
	v_mul_f32_e32 v0, v43, v0
	v_rcp_f32_e32 v43, v48
	s_nop 0
	v_mul_f32_e32 v42, v42, v43
	v_cvt_pk_bf16_f32 v42, v42, v0
	v_mul_f32_e32 v0, 0xbfb8aa3b, v44
	v_exp_f32_e32 v48, v0
	v_mul_f32_e32 v0, 0xbfb8aa3b, v45
	v_exp_f32_e32 v49, v0
	s_nop 0
	v_pk_add_f32 v[48:49], v[48:49], 1.0 op_sel_hi:[1,0]
	s_nop 0
	v_rcp_f32_e32 v0, v49
	s_nop 0
	v_mul_f32_e32 v0, v45, v0
	v_rcp_f32_e32 v43, v48
	s_nop 0
	v_mul_f32_e32 v43, v44, v43
	v_cvt_pk_bf16_f32 v43, v43, v0
	v_add_u32_e32 v0, 0x1000, v66
	ds_write2_b64 v0, v[46:47], v[42:43] offset0:32 offset1:36
	v_mul_f32_e32 v42, 0xbfb8aa3b, v38
	v_mul_f32_e32 v43, 0xbfb8aa3b, v39
	v_exp_f32_e32 v42, v42
	v_exp_f32_e32 v43, v43
	s_nop 0
	v_pk_add_f32 v[42:43], v[42:43], 1.0 op_sel_hi:[1,0]
	s_nop 0
	v_rcp_f32_e32 v44, v43
	s_nop 0
	v_mul_f32_e32 v39, v39, v44
	v_rcp_f32_e32 v43, v42
	s_nop 0
	v_mul_f32_e32 v38, v38, v43
	v_cvt_pk_bf16_f32 v38, v38, v39
	v_mul_f32_e32 v39, 0xbfb8aa3b, v40
	v_exp_f32_e32 v42, v39
	v_mul_f32_e32 v39, 0xbfb8aa3b, v41
	v_exp_f32_e32 v43, v39
	s_nop 0
	v_pk_add_f32 v[42:43], v[42:43], 1.0 op_sel_hi:[1,0]
	s_nop 0
	v_rcp_f32_e32 v39, v43
	s_nop 0
	v_mul_f32_e32 v39, v41, v39
	v_rcp_f32_e32 v41, v42
	s_nop 0
	v_mul_f32_e32 v40, v40, v41
	v_cvt_pk_bf16_f32 v39, v40, v39
	v_mul_f32_e32 v40, 0xbfb8aa3b, v34
	v_mul_f32_e32 v41, 0xbfb8aa3b, v35
	v_exp_f32_e32 v40, v40
	v_exp_f32_e32 v41, v41
	s_nop 0
	v_pk_add_f32 v[40:41], v[40:41], 1.0 op_sel_hi:[1,0]
	s_nop 0
	v_rcp_f32_e32 v42, v41
	s_nop 0
	v_mul_f32_e32 v35, v35, v42
	v_rcp_f32_e32 v41, v40
	s_nop 0
	v_mul_f32_e32 v34, v34, v41
	v_cvt_pk_bf16_f32 v34, v34, v35
	v_mul_f32_e32 v35, 0xbfb8aa3b, v36
	v_exp_f32_e32 v40, v35
	v_mul_f32_e32 v35, 0xbfb8aa3b, v37
	v_exp_f32_e32 v41, v35
	s_nop 0
	v_pk_add_f32 v[40:41], v[40:41], 1.0 op_sel_hi:[1,0]
	s_nop 0
	v_rcp_f32_e32 v35, v41
	s_nop 0
	v_mul_f32_e32 v35, v37, v35
	v_rcp_f32_e32 v37, v40
	s_nop 0
	v_mul_f32_e32 v36, v36, v37
	v_cvt_pk_bf16_f32 v35, v36, v35
	ds_write2_b64 v0, v[38:39], v[34:35] offset0:40 offset1:44
	v_mul_f32_e32 v0, 0xbfb8aa3b, v30
	v_exp_f32_e32 v34, v0
	v_mul_f32_e32 v0, 0xbfb8aa3b, v31
	v_exp_f32_e32 v35, v0
	s_nop 0
	v_pk_add_f32 v[34:35], v[34:35], 1.0 op_sel_hi:[1,0]
	s_nop 0
	v_rcp_f32_e32 v0, v35
	s_nop 0
	v_mul_f32_e32 v0, v31, v0
	v_rcp_f32_e32 v31, v34
	s_nop 0
	v_mul_f32_e32 v30, v30, v31
	v_cvt_pk_bf16_f32 v30, v30, v0
	v_mul_f32_e32 v0, 0xbfb8aa3b, v32
	v_exp_f32_e32 v34, v0
	v_mul_f32_e32 v0, 0xbfb8aa3b, v33
	v_exp_f32_e32 v35, v0
	s_nop 0
	v_pk_add_f32 v[34:35], v[34:35], 1.0 op_sel_hi:[1,0]
	s_nop 0
	v_rcp_f32_e32 v0, v35
	s_nop 0
	v_mul_f32_e32 v0, v33, v0
	v_rcp_f32_e32 v31, v34
	s_nop 0
	v_mul_f32_e32 v31, v32, v31
	v_cvt_pk_bf16_f32 v31, v31, v0
	v_mul_f32_e32 v0, 0xbfb8aa3b, v26
	v_exp_f32_e32 v32, v0
	v_mul_f32_e32 v0, 0xbfb8aa3b, v27
	v_exp_f32_e32 v33, v0
	s_nop 0
	v_pk_add_f32 v[32:33], v[32:33], 1.0 op_sel_hi:[1,0]
	s_nop 0
	v_rcp_f32_e32 v0, v33
	s_nop 0
	v_mul_f32_e32 v0, v27, v0
	v_rcp_f32_e32 v27, v32
	s_nop 0
	v_mul_f32_e32 v26, v26, v27
	v_cvt_pk_bf16_f32 v26, v26, v0
	v_mul_f32_e32 v0, 0xbfb8aa3b, v28
	v_exp_f32_e32 v32, v0
	v_mul_f32_e32 v0, 0xbfb8aa3b, v29
	v_exp_f32_e32 v33, v0
	s_nop 0
	v_pk_add_f32 v[32:33], v[32:33], 1.0 op_sel_hi:[1,0]
	s_nop 0
	v_rcp_f32_e32 v0, v33
	s_nop 0
	v_mul_f32_e32 v0, v29, v0
	v_rcp_f32_e32 v27, v32
	s_nop 0
	v_mul_f32_e32 v27, v28, v27
	v_cvt_pk_bf16_f32 v27, v27, v0
	v_add_u32_e32 v0, 0x2000, v66
	ds_write2_b64 v0, v[30:31], v[26:27] offset0:64 offset1:68
	v_mul_f32_e32 v26, 0xbfb8aa3b, v22
	v_mul_f32_e32 v27, 0xbfb8aa3b, v23
	v_exp_f32_e32 v26, v26
	v_exp_f32_e32 v27, v27
	s_nop 0
	v_pk_add_f32 v[26:27], v[26:27], 1.0 op_sel_hi:[1,0]
	s_nop 0
	v_rcp_f32_e32 v28, v27
	s_nop 0
	v_mul_f32_e32 v23, v23, v28
	v_rcp_f32_e32 v27, v26
	s_nop 0
	v_mul_f32_e32 v22, v22, v27
	v_cvt_pk_bf16_f32 v22, v22, v23
	v_mul_f32_e32 v23, 0xbfb8aa3b, v24
	v_exp_f32_e32 v26, v23
	v_mul_f32_e32 v23, 0xbfb8aa3b, v25
	v_exp_f32_e32 v27, v23
	s_nop 0
	v_pk_add_f32 v[26:27], v[26:27], 1.0 op_sel_hi:[1,0]
	s_nop 0
	v_rcp_f32_e32 v23, v27
	s_nop 0
	v_mul_f32_e32 v23, v25, v23
	v_rcp_f32_e32 v25, v26
	s_nop 0
	v_mul_f32_e32 v24, v24, v25
	v_cvt_pk_bf16_f32 v23, v24, v23
	v_mul_f32_e32 v24, 0xbfb8aa3b, v18
	v_mul_f32_e32 v25, 0xbfb8aa3b, v19
	v_exp_f32_e32 v24, v24
	v_exp_f32_e32 v25, v25
	s_nop 0
	v_pk_add_f32 v[24:25], v[24:25], 1.0 op_sel_hi:[1,0]
	s_nop 0
	v_rcp_f32_e32 v26, v25
	s_nop 0
	v_mul_f32_e32 v19, v19, v26
	v_rcp_f32_e32 v25, v24
	s_nop 0
	v_mul_f32_e32 v18, v18, v25
	v_cvt_pk_bf16_f32 v18, v18, v19
	v_mul_f32_e32 v19, 0xbfb8aa3b, v20
	v_exp_f32_e32 v24, v19
	v_mul_f32_e32 v19, 0xbfb8aa3b, v21
	v_exp_f32_e32 v25, v19
	s_nop 0
	v_pk_add_f32 v[24:25], v[24:25], 1.0 op_sel_hi:[1,0]
	s_nop 0
	v_rcp_f32_e32 v19, v25
	s_nop 0
	v_mul_f32_e32 v19, v21, v19
	v_rcp_f32_e32 v21, v24
	s_nop 0
	v_mul_f32_e32 v20, v20, v21
	v_cvt_pk_bf16_f32 v19, v20, v19
	ds_write2_b64 v0, v[22:23], v[18:19] offset0:72 offset1:76
	v_mul_f32_e32 v0, 0xbfb8aa3b, v14
	v_exp_f32_e32 v18, v0
	v_mul_f32_e32 v0, 0xbfb8aa3b, v15
	v_exp_f32_e32 v19, v0
	s_nop 0
	v_pk_add_f32 v[18:19], v[18:19], 1.0 op_sel_hi:[1,0]
	s_nop 0
	v_rcp_f32_e32 v0, v19
	s_nop 0
	v_mul_f32_e32 v0, v15, v0
	v_rcp_f32_e32 v15, v18
	s_nop 0
	v_mul_f32_e32 v14, v14, v15
	v_cvt_pk_bf16_f32 v14, v14, v0
	v_mul_f32_e32 v0, 0xbfb8aa3b, v16
	v_exp_f32_e32 v18, v0
	v_mul_f32_e32 v0, 0xbfb8aa3b, v17
	v_exp_f32_e32 v19, v0
	s_nop 0
	v_pk_add_f32 v[18:19], v[18:19], 1.0 op_sel_hi:[1,0]
	s_nop 0
	v_rcp_f32_e32 v0, v19
	s_nop 0
	v_mul_f32_e32 v0, v17, v0
	v_rcp_f32_e32 v15, v18
	s_nop 0
	v_mul_f32_e32 v15, v16, v15
	v_cvt_pk_bf16_f32 v15, v15, v0
	v_mul_f32_e32 v0, 0xbfb8aa3b, v10
	v_exp_f32_e32 v16, v0
	v_mul_f32_e32 v0, 0xbfb8aa3b, v11
	v_exp_f32_e32 v17, v0
	s_nop 0
	v_pk_add_f32 v[16:17], v[16:17], 1.0 op_sel_hi:[1,0]
	s_nop 0
	v_rcp_f32_e32 v0, v17
	s_nop 0
	v_mul_f32_e32 v0, v11, v0
	v_rcp_f32_e32 v11, v16
	s_nop 0
	v_mul_f32_e32 v10, v10, v11
	v_cvt_pk_bf16_f32 v10, v10, v0
	v_mul_f32_e32 v0, 0xbfb8aa3b, v12
	v_exp_f32_e32 v16, v0
	v_mul_f32_e32 v0, 0xbfb8aa3b, v13
	v_exp_f32_e32 v17, v0
	s_nop 0
	v_pk_add_f32 v[16:17], v[16:17], 1.0 op_sel_hi:[1,0]
	s_nop 0
	v_rcp_f32_e32 v0, v17
	s_nop 0
	v_mul_f32_e32 v0, v13, v0
	v_rcp_f32_e32 v11, v16
	s_nop 0
	v_mul_f32_e32 v11, v12, v11
	v_cvt_pk_bf16_f32 v11, v11, v0
	v_add_u32_e32 v0, 0x3000, v66
	ds_write2_b64 v0, v[14:15], v[10:11] offset0:96 offset1:100
	v_mul_f32_e32 v10, 0xbfb8aa3b, v6
	v_mul_f32_e32 v11, 0xbfb8aa3b, v7
	v_exp_f32_e32 v10, v10
	v_exp_f32_e32 v11, v11
	s_nop 0
	v_pk_add_f32 v[10:11], v[10:11], 1.0 op_sel_hi:[1,0]
	s_nop 0
	v_rcp_f32_e32 v12, v11
	s_nop 0
	v_mul_f32_e32 v7, v7, v12
	v_rcp_f32_e32 v11, v10
	s_nop 0
	v_mul_f32_e32 v6, v6, v11
	v_cvt_pk_bf16_f32 v6, v6, v7
	v_mul_f32_e32 v7, 0xbfb8aa3b, v8
	v_exp_f32_e32 v10, v7
	v_mul_f32_e32 v7, 0xbfb8aa3b, v9
	v_exp_f32_e32 v11, v7
	s_nop 0
	v_pk_add_f32 v[10:11], v[10:11], 1.0 op_sel_hi:[1,0]
	s_nop 0
	v_rcp_f32_e32 v7, v11
	s_nop 0
	v_mul_f32_e32 v7, v9, v7
	v_rcp_f32_e32 v9, v10
	s_nop 0
	v_mul_f32_e32 v8, v8, v9
	v_cvt_pk_bf16_f32 v7, v8, v7
	v_mul_f32_e32 v8, 0xbfb8aa3b, v2
	v_mul_f32_e32 v9, 0xbfb8aa3b, v3
	v_exp_f32_e32 v8, v8
	v_exp_f32_e32 v9, v9
	s_nop 0
	v_pk_add_f32 v[8:9], v[8:9], 1.0 op_sel_hi:[1,0]
	s_nop 0
	v_rcp_f32_e32 v10, v9
	s_nop 0
	v_mul_f32_e32 v3, v3, v10
	v_rcp_f32_e32 v9, v8
	s_nop 0
	v_mul_f32_e32 v2, v2, v9
	v_cvt_pk_bf16_f32 v2, v2, v3
	v_mul_f32_e32 v3, 0xbfb8aa3b, v4
	v_exp_f32_e32 v8, v3
	v_mul_f32_e32 v3, 0xbfb8aa3b, v5
	v_exp_f32_e32 v9, v3
	s_nop 0
	v_pk_add_f32 v[8:9], v[8:9], 1.0 op_sel_hi:[1,0]
	s_nop 0
	v_rcp_f32_e32 v3, v9
	s_nop 0
	v_mul_f32_e32 v3, v5, v3
	v_rcp_f32_e32 v5, v8
	s_nop 0
	v_mul_f32_e32 v4, v4, v5
	v_cvt_pk_bf16_f32 v3, v4, v3
	ds_write2_b64 v0, v[6:7], v[2:3] offset0:104 offset1:108
	s_waitcnt lgkmcnt(0)
	s_barrier

.LBB0_271:
	v_mov_b32_e32 v0, v151
	s_movk_i32 s4, 0xff80
	v_lshrrev_b32_e32 v66, 1, v0
	v_and_b32_e32 v66, 24, v66
	v_and_b32_e32 v68, 0x4f, v0
	v_and_or_b32 v0, v0, s4, v66
	v_mul_f32_e32 v66, 0xbfb8aa3b, v62
	v_mul_f32_e32 v67, 0xbfb8aa3b, v63
	v_exp_f32_e32 v66, v66
	v_exp_f32_e32 v67, v67
	s_nop 0
	v_pk_add_f32 v[66:67], v[66:67], 1.0 op_sel_hi:[1,0]
	s_nop 0
	v_rcp_f32_e32 v69, v67
	s_nop 0
	v_mul_f32_e32 v63, v63, v69
	v_rcp_f32_e32 v67, v66
	s_nop 0
	v_mul_f32_e32 v62, v62, v67
	v_cvt_pk_bf16_f32 v62, v62, v63
	v_mul_f32_e32 v63, 0xbfb8aa3b, v64
	v_exp_f32_e32 v66, v63
	v_mul_f32_e32 v63, 0xbfb8aa3b, v65
	v_exp_f32_e32 v67, v63
	s_nop 0
	v_pk_add_f32 v[66:67], v[66:67], 1.0 op_sel_hi:[1,0]
	s_nop 0
	v_rcp_f32_e32 v63, v67
	s_nop 0
	v_mul_f32_e32 v63, v65, v63
	v_div_scale_f32 v65, s[4:5], v66, v66, v64
	v_rcp_f32_e32 v67, v65
	s_movk_i32 s4, 0x110
	v_mad_u32_u24 v0, v68, s4, v0
	v_fma_f32 v69, -v65, v67, 1.0
	v_fmac_f32_e32 v67, v69, v67
	v_div_scale_f32 v69, vcc, v64, v66, v64
	v_mul_f32_e32 v70, v69, v67
	v_fma_f32 v71, -v65, v70, v69
	v_fmac_f32_e32 v70, v71, v67
	v_fma_f32 v65, -v65, v70, v69
	v_div_fmas_f32 v65, v65, v67, v70
	v_div_fixup_f32 v64, v65, v66, v64
	v_cvt_pk_bf16_f32 v63, v64, v63
	v_mul_f32_e32 v64, 0xbfb8aa3b, v58
	v_mul_f32_e32 v65, 0xbfb8aa3b, v59
	v_exp_f32_e32 v64, v64
	v_exp_f32_e32 v65, v65
	s_nop 0
	v_pk_add_f32 v[64:65], v[64:65], 1.0 op_sel_hi:[1,0]
	s_nop 0
	v_rcp_f32_e32 v66, v65
	s_nop 0
	v_mul_f32_e32 v59, v59, v66
	v_rcp_f32_e32 v65, v64
	s_nop 0
	v_mul_f32_e32 v58, v58, v65
	v_cvt_pk_bf16_f32 v58, v58, v59
	v_mul_f32_e32 v59, 0xbfb8aa3b, v60
	v_exp_f32_e32 v64, v59
	v_mul_f32_e32 v59, 0xbfb8aa3b, v61
	v_exp_f32_e32 v65, v59
	s_nop 0
	v_pk_add_f32 v[64:65], v[64:65], 1.0 op_sel_hi:[1,0]
	s_nop 0
	v_rcp_f32_e32 v59, v65
	s_nop 0
	v_mul_f32_e32 v59, v61, v59
	v_rcp_f32_e32 v61, v64
	s_nop 0
	v_mul_f32_e32 v60, v60, v61
	v_cvt_pk_bf16_f32 v59, v60, v59
	v_mul_f32_e32 v60, 0xbfb8aa3b, v54
	v_mul_f32_e32 v61, 0xbfb8aa3b, v55
	v_exp_f32_e32 v60, v60
	v_exp_f32_e32 v61, v61
	s_nop 0
	v_pk_add_f32 v[60:61], v[60:61], 1.0 op_sel_hi:[1,0]
	s_nop 0
	v_rcp_f32_e32 v64, v61
	s_nop 0
	v_mul_f32_e32 v55, v55, v64
	v_rcp_f32_e32 v61, v60
	s_nop 0
	v_mul_f32_e32 v54, v54, v61
	v_cvt_pk_bf16_f32 v54, v54, v55
	v_mul_f32_e32 v55, 0xbfb8aa3b, v56
	v_exp_f32_e32 v60, v55
	v_mul_f32_e32 v55, 0xbfb8aa3b, v57
	v_exp_f32_e32 v61, v55
	s_nop 0
	v_pk_add_f32 v[60:61], v[60:61], 1.0 op_sel_hi:[1,0]
	s_nop 0
	v_rcp_f32_e32 v55, v61
	s_nop 0
	v_mul_f32_e32 v55, v57, v55
	v_rcp_f32_e32 v57, v60
	s_nop 0
	v_mul_f32_e32 v56, v56, v57
	v_cvt_pk_bf16_f32 v55, v56, v55
	v_mul_f32_e32 v56, 0xbfb8aa3b, v50
	v_mul_f32_e32 v57, 0xbfb8aa3b, v51
	v_exp_f32_e32 v56, v56
	v_exp_f32_e32 v57, v57
	s_nop 0
	v_pk_add_f32 v[56:57], v[56:57], 1.0 op_sel_hi:[1,0]
	s_nop 0
	v_rcp_f32_e32 v60, v57
	s_nop 0
	v_mul_f32_e32 v51, v51, v60
	v_rcp_f32_e32 v57, v56
	s_nop 0
	v_mul_f32_e32 v50, v50, v57
	v_cvt_pk_bf16_f32 v50, v50, v51
	v_mul_f32_e32 v51, 0xbfb8aa3b, v52
	v_exp_f32_e32 v56, v51
	v_mul_f32_e32 v51, 0xbfb8aa3b, v53
	v_exp_f32_e32 v57, v51
	s_nop 0
	v_pk_add_f32 v[56:57], v[56:57], 1.0 op_sel_hi:[1,0]
	s_nop 0
	v_rcp_f32_e32 v51, v57
	s_nop 0
	v_mul_f32_e32 v51, v53, v51
	v_rcp_f32_e32 v53, v56
	s_nop 0
	v_mul_f32_e32 v52, v52, v53
	v_cvt_pk_bf16_f32 v51, v52, v51
	v_mul_f32_e32 v52, 0xbfb8aa3b, v46
	v_mul_f32_e32 v53, 0xbfb8aa3b, v47
	v_exp_f32_e32 v52, v52
	v_exp_f32_e32 v53, v53
	s_nop 0
	v_pk_add_f32 v[52:53], v[52:53], 1.0 op_sel_hi:[1,0]
	s_nop 0
	v_rcp_f32_e32 v56, v53
	s_nop 0
	v_mul_f32_e32 v47, v47, v56
	v_rcp_f32_e32 v53, v52
	s_nop 0
	v_mul_f32_e32 v46, v46, v53
	v_cvt_pk_bf16_f32 v46, v46, v47
	v_mul_f32_e32 v47, 0xbfb8aa3b, v48
	v_exp_f32_e32 v52, v47
	v_mul_f32_e32 v47, 0xbfb8aa3b, v49
	v_exp_f32_e32 v53, v47
	s_nop 0
	v_pk_add_f32 v[52:53], v[52:53], 1.0 op_sel_hi:[1,0]
	s_nop 0
	v_rcp_f32_e32 v47, v53
	s_nop 0
	v_mul_f32_e32 v47, v49, v47
	v_rcp_f32_e32 v49, v52
	s_nop 0
	v_mul_f32_e32 v48, v48, v49
	v_cvt_pk_bf16_f32 v47, v48, v47
	ds_write2_b64 v0, v[62:63], v[46:47] offset1:4
	v_mul_f32_e32 v46, 0xbfb8aa3b, v42
	v_mul_f32_e32 v47, 0xbfb8aa3b, v43
	v_exp_f32_e32 v46, v46
	v_exp_f32_e32 v47, v47
	s_nop 0
	v_pk_add_f32 v[46:47], v[46:47], 1.0 op_sel_hi:[1,0]
	s_nop 0
	v_rcp_f32_e32 v48, v47
	s_nop 0
	v_mul_f32_e32 v43, v43, v48
	v_rcp_f32_e32 v47, v46
	s_nop 0
	v_mul_f32_e32 v42, v42, v47
	v_cvt_pk_bf16_f32 v46, v42, v43
	v_mul_f32_e32 v42, 0xbfb8aa3b, v44
	v_mul_f32_e32 v43, 0xbfb8aa3b, v45
	v_exp_f32_e32 v42, v42
	v_exp_f32_e32 v43, v43
	s_nop 0
	v_pk_add_f32 v[42:43], v[42:43], 1.0 op_sel_hi:[1,0]
	s_nop 0
	v_rcp_f32_e32 v47, v43
	s_nop 0
	v_mul_f32_e32 v43, v45, v47
	v_rcp_f32_e32 v45, v42
	s_nop 0
	v_mul_f32_e32 v42, v44, v45
	v_cvt_pk_bf16_f32 v47, v42, v43
	v_mul_f32_e32 v43, 0xbfb8aa3b, v38
	v_exp_f32_e32 v44, v43
	v_mul_f32_e32 v43, 0xbfb8aa3b, v39
	v_exp_f32_e32 v45, v43
	v_add_u32_e32 v42, 0x1000, v0
	ds_write2_b64 v42, v[58:59], v[46:47] offset0:32 offset1:36
	v_pk_add_f32 v[44:45], v[44:45], 1.0 op_sel_hi:[1,0]
	s_nop 0
	v_rcp_f32_e32 v43, v45
	s_nop 0
	v_mul_f32_e32 v39, v39, v43
	v_rcp_f32_e32 v43, v44
	s_nop 0
	v_mul_f32_e32 v38, v38, v43
	v_cvt_pk_bf16_f32 v44, v38, v39
	v_mul_f32_e32 v38, 0xbfb8aa3b, v40
	v_mul_f32_e32 v39, 0xbfb8aa3b, v41
	v_exp_f32_e32 v38, v38
	v_exp_f32_e32 v39, v39
	s_nop 0
	v_pk_add_f32 v[38:39], v[38:39], 1.0 op_sel_hi:[1,0]
	s_nop 0
	v_rcp_f32_e32 v43, v39
	s_nop 0
	v_mul_f32_e32 v39, v41, v43
	v_rcp_f32_e32 v41, v38
	s_nop 0
	v_mul_f32_e32 v38, v40, v41
	v_cvt_pk_bf16_f32 v45, v38, v39
	v_mul_f32_e32 v39, 0xbfb8aa3b, v34
	v_exp_f32_e32 v40, v39
	v_mul_f32_e32 v39, 0xbfb8aa3b, v35
	v_exp_f32_e32 v41, v39
	v_add_u32_e32 v38, 0x2000, v0
	ds_write2_b64 v38, v[54:55], v[44:45] offset0:64 offset1:68
	v_pk_add_f32 v[40:41], v[40:41], 1.0 op_sel_hi:[1,0]
	s_nop 0
	v_rcp_f32_e32 v39, v41
	s_nop 0
	v_mul_f32_e32 v35, v35, v39
	v_rcp_f32_e32 v39, v40
	s_nop 0
	v_mul_f32_e32 v34, v34, v39
	v_cvt_pk_bf16_f32 v40, v34, v35
	v_mul_f32_e32 v34, 0xbfb8aa3b, v36
	v_mul_f32_e32 v35, 0xbfb8aa3b, v37
	v_exp_f32_e32 v34, v34
	v_exp_f32_e32 v35, v35
	s_nop 0
	v_pk_add_f32 v[34:35], v[34:35], 1.0 op_sel_hi:[1,0]
	s_nop 0
	v_rcp_f32_e32 v39, v35
	s_nop 0
	v_mul_f32_e32 v35, v37, v39
	v_rcp_f32_e32 v37, v34
	s_nop 0
	v_mul_f32_e32 v34, v36, v37
	v_cvt_pk_bf16_f32 v41, v34, v35
	v_mul_f32_e32 v35, 0xbfb8aa3b, v30
	v_exp_f32_e32 v36, v35
	v_mul_f32_e32 v35, 0xbfb8aa3b, v31
	v_exp_f32_e32 v37, v35
	v_add_u32_e32 v34, 0x3000, v0
	ds_write2_b64 v34, v[50:51], v[40:41] offset0:96 offset1:100
	v_pk_add_f32 v[36:37], v[36:37], 1.0 op_sel_hi:[1,0]
	s_nop 0
	v_rcp_f32_e32 v35, v37
	s_nop 0
	v_mul_f32_e32 v31, v31, v35
	v_rcp_f32_e32 v35, v36
	s_nop 0
	v_mul_f32_e32 v30, v30, v35
	v_cvt_pk_bf16_f32 v30, v30, v31
	v_mul_f32_e32 v31, 0xbfb8aa3b, v32
	v_exp_f32_e32 v36, v31
	v_mul_f32_e32 v31, 0xbfb8aa3b, v33
	v_exp_f32_e32 v37, v31
	s_nop 0
	v_pk_add_f32 v[36:37], v[36:37], 1.0 op_sel_hi:[1,0]
	s_nop 0
	v_rcp_f32_e32 v31, v37
	s_nop 0
	v_mul_f32_e32 v31, v33, v31
	v_rcp_f32_e32 v33, v36
	s_nop 0
	v_mul_f32_e32 v32, v32, v33
	v_cvt_pk_bf16_f32 v31, v32, v31
	v_mul_f32_e32 v32, 0xbfb8aa3b, v26
	v_mul_f32_e32 v33, 0xbfb8aa3b, v27
	v_exp_f32_e32 v32, v32
	v_exp_f32_e32 v33, v33
	s_nop 0
	v_pk_add_f32 v[32:33], v[32:33], 1.0 op_sel_hi:[1,0]
	s_nop 0
	v_rcp_f32_e32 v35, v33
	s_nop 0
	v_mul_f32_e32 v27, v27, v35
	v_rcp_f32_e32 v33, v32
	s_nop 0
	v_mul_f32_e32 v26, v26, v33
	v_cvt_pk_bf16_f32 v26, v26, v27
	v_mul_f32_e32 v27, 0xbfb8aa3b, v28
	v_exp_f32_e32 v32, v27
	v_mul_f32_e32 v27, 0xbfb8aa3b, v29
	v_exp_f32_e32 v33, v27
	s_nop 0
	v_pk_add_f32 v[32:33], v[32:33], 1.0 op_sel_hi:[1,0]
	s_nop 0
	v_rcp_f32_e32 v27, v33
	s_nop 0
	v_mul_f32_e32 v27, v29, v27
	v_rcp_f32_e32 v29, v32
	s_nop 0
	v_mul_f32_e32 v28, v28, v29
	v_cvt_pk_bf16_f32 v27, v28, v27
	v_mul_f32_e32 v28, 0xbfb8aa3b, v22
	v_mul_f32_e32 v29, 0xbfb8aa3b, v23
	v_exp_f32_e32 v28, v28
	v_exp_f32_e32 v29, v29
	s_nop 0
	v_pk_add_f32 v[28:29], v[28:29], 1.0 op_sel_hi:[1,0]
	s_nop 0
	v_rcp_f32_e32 v32, v29
	s_nop 0
	v_mul_f32_e32 v23, v23, v32
	v_rcp_f32_e32 v29, v28
	s_nop 0
	v_mul_f32_e32 v22, v22, v29
	v_cvt_pk_bf16_f32 v22, v22, v23
	v_mul_f32_e32 v23, 0xbfb8aa3b, v24
	v_exp_f32_e32 v28, v23
	v_mul_f32_e32 v23, 0xbfb8aa3b, v25
	v_exp_f32_e32 v29, v23
	s_nop 0
	v_pk_add_f32 v[28:29], v[28:29], 1.0 op_sel_hi:[1,0]
	s_nop 0
	v_rcp_f32_e32 v23, v29
	s_nop 0
	v_mul_f32_e32 v23, v25, v23
	v_rcp_f32_e32 v25, v28
	s_nop 0
	v_mul_f32_e32 v24, v24, v25
	v_cvt_pk_bf16_f32 v23, v24, v23
	v_mul_f32_e32 v24, 0xbfb8aa3b, v18
	v_mul_f32_e32 v25, 0xbfb8aa3b, v19
	v_exp_f32_e32 v24, v24
	v_exp_f32_e32 v25, v25
	s_nop 0
	v_pk_add_f32 v[24:25], v[24:25], 1.0 op_sel_hi:[1,0]
	s_nop 0
	v_rcp_f32_e32 v28, v25
	s_nop 0
	v_mul_f32_e32 v19, v19, v28
	v_rcp_f32_e32 v25, v24
	s_nop 0
	v_mul_f32_e32 v18, v18, v25
	v_cvt_pk_bf16_f32 v18, v18, v19
	v_mul_f32_e32 v19, 0xbfb8aa3b, v20
	v_exp_f32_e32 v24, v19
	v_mul_f32_e32 v19, 0xbfb8aa3b, v21
	v_exp_f32_e32 v25, v19
	s_nop 0
	v_pk_add_f32 v[24:25], v[24:25], 1.0 op_sel_hi:[1,0]
	s_nop 0
	v_rcp_f32_e32 v19, v25
	s_nop 0
	v_mul_f32_e32 v19, v21, v19
	v_rcp_f32_e32 v21, v24
	s_nop 0
	v_mul_f32_e32 v20, v20, v21
	v_cvt_pk_bf16_f32 v19, v20, v19
	v_mul_f32_e32 v20, 0xbfb8aa3b, v14
	v_mul_f32_e32 v21, 0xbfb8aa3b, v15
	v_exp_f32_e32 v20, v20
	v_exp_f32_e32 v21, v21
	s_nop 0
	v_pk_add_f32 v[20:21], v[20:21], 1.0 op_sel_hi:[1,0]
	s_nop 0
	v_rcp_f32_e32 v24, v21
	s_nop 0
	v_mul_f32_e32 v15, v15, v24
	v_rcp_f32_e32 v21, v20
	s_nop 0
	v_mul_f32_e32 v14, v14, v21
	v_cvt_pk_bf16_f32 v14, v14, v15
	v_mul_f32_e32 v15, 0xbfb8aa3b, v16
	v_exp_f32_e32 v20, v15
	v_mul_f32_e32 v15, 0xbfb8aa3b, v17
	v_exp_f32_e32 v21, v15
	s_nop 0
	v_pk_add_f32 v[20:21], v[20:21], 1.0 op_sel_hi:[1,0]
	s_nop 0
	v_rcp_f32_e32 v15, v21
	s_nop 0
	v_mul_f32_e32 v15, v17, v15
	v_rcp_f32_e32 v17, v20
	s_nop 0
	v_mul_f32_e32 v16, v16, v17
	v_cvt_pk_bf16_f32 v15, v16, v15
	ds_write2_b64 v0, v[30:31], v[14:15] offset0:8 offset1:12
	v_mul_f32_e32 v0, 0xbfb8aa3b, v10
	v_exp_f32_e32 v14, v0
	v_mul_f32_e32 v0, 0xbfb8aa3b, v11
	v_exp_f32_e32 v15, v0
	s_nop 0
	v_pk_add_f32 v[14:15], v[14:15], 1.0 op_sel_hi:[1,0]
	s_nop 0
	v_rcp_f32_e32 v0, v15
	s_nop 0
	v_mul_f32_e32 v0, v11, v0
	v_rcp_f32_e32 v11, v14
	s_nop 0
	v_mul_f32_e32 v10, v10, v11
	v_cvt_pk_bf16_f32 v10, v10, v0
	v_mul_f32_e32 v0, 0xbfb8aa3b, v12
	v_exp_f32_e32 v14, v0
	v_mul_f32_e32 v0, 0xbfb8aa3b, v13
	v_exp_f32_e32 v15, v0
	s_nop 0
	v_pk_add_f32 v[14:15], v[14:15], 1.0 op_sel_hi:[1,0]
	s_nop 0
	v_rcp_f32_e32 v0, v15
	s_nop 0
	v_mul_f32_e32 v0, v13, v0
	v_rcp_f32_e32 v11, v14
	s_nop 0
	v_mul_f32_e32 v11, v12, v11
	v_cvt_pk_bf16_f32 v11, v11, v0
	v_mul_f32_e32 v0, 0xbfb8aa3b, v6
	ds_write2_b64 v42, v[26:27], v[10:11] offset0:40 offset1:44
	v_exp_f32_e32 v10, v0
	v_mul_f32_e32 v0, 0xbfb8aa3b, v7
	v_exp_f32_e32 v11, v0
	s_nop 0
	v_pk_add_f32 v[10:11], v[10:11], 1.0 op_sel_hi:[1,0]
	s_nop 0
	v_rcp_f32_e32 v0, v11
	s_nop 0
	v_mul_f32_e32 v0, v7, v0
	v_rcp_f32_e32 v7, v10
	s_nop 0
	v_mul_f32_e32 v6, v6, v7
	v_cvt_pk_bf16_f32 v6, v6, v0
	v_mul_f32_e32 v0, 0xbfb8aa3b, v8
	v_exp_f32_e32 v10, v0
	v_mul_f32_e32 v0, 0xbfb8aa3b, v9
	v_exp_f32_e32 v11, v0
	s_nop 0
	v_pk_add_f32 v[10:11], v[10:11], 1.0 op_sel_hi:[1,0]
	s_nop 0
	v_rcp_f32_e32 v0, v11
	s_nop 0
	v_mul_f32_e32 v0, v9, v0
	v_rcp_f32_e32 v7, v10
	s_nop 0
	v_mul_f32_e32 v7, v8, v7
	v_cvt_pk_bf16_f32 v7, v7, v0
	v_mul_f32_e32 v0, 0xbfb8aa3b, v2
	ds_write2_b64 v38, v[22:23], v[6:7] offset0:72 offset1:76
	v_exp_f32_e32 v6, v0
	v_mul_f32_e32 v0, 0xbfb8aa3b, v3
	v_exp_f32_e32 v7, v0
	s_nop 0
	v_pk_add_f32 v[6:7], v[6:7], 1.0 op_sel_hi:[1,0]
	s_nop 0
	v_rcp_f32_e32 v0, v7
	s_nop 0
	v_mul_f32_e32 v0, v3, v0
	v_rcp_f32_e32 v3, v6
	s_nop 0
	v_mul_f32_e32 v2, v2, v3
	v_cvt_pk_bf16_f32 v2, v2, v0
	v_mul_f32_e32 v0, 0xbfb8aa3b, v4
	v_exp_f32_e32 v6, v0
	v_mul_f32_e32 v0, 0xbfb8aa3b, v5
	v_exp_f32_e32 v7, v0
	s_nop 0
	v_pk_add_f32 v[6:7], v[6:7], 1.0 op_sel_hi:[1,0]
	s_nop 0
	v_rcp_f32_e32 v0, v7
	s_nop 0
	v_mul_f32_e32 v0, v5, v0
	v_rcp_f32_e32 v3, v6
	s_nop 0
	v_mul_f32_e32 v3, v4, v3
	v_cvt_pk_bf16_f32 v3, v3, v0
	ds_write2_b64 v34, v[18:19], v[2:3] offset0:104 offset1:108
	s_waitcnt lgkmcnt(0)
	s_barrier
	s_mov_b64 s[38:39], -1
	s_and_b64 vcc, exec, s[28:29]
	s_cbranch_vccz .LBB0_269
